# hand-written LayerNorm latent-row loop (LDS modulation table, prefetch, no store-serialised waits) replacing hipcc 4-row loop at both LN sites
# speedup vs baseline: 1.0072x; 1.0072x over previous
; __device__ __forceinline__ unsigned pk2(float lo, float hi) { return f2bf(lo) | (f2bf(hi) << 16); }
; template <int NR> __device__ __forceinline__ void ln_lat_body(float* xL, const float* g, const float* b, const float* modp, bf16* U, int m0, int ngw, int lane, float* dummy, const bf16* vin, bf16* xB) {
;     {
;         f32x4 v[NR][4]; float s[NR], s2[NR];
; #pragma unroll
;         for (int q = 0; q < NR; ++q)
; #pragma unroll
;             for (int jj = 0; jj < 2; ++jj) { const size_t o_ = (size_t)(m0 + q * ngw) * DM + 8 * lane + 512 * jj;
;                 if (vin) { const v4u w = *(const v4u*)(vin + o_); v[q][2 * jj] = (f32x4){bflo(w.x), bfhi(w.x), bflo(w.y), bfhi(w.y)}; v[q][2 * jj + 1] = (f32x4){bflo(w.z), bfhi(w.z), bflo(w.w), bfhi(w.w)}; }
;                 else { v[q][2 * jj] = *(const f32x4*)(xL + o_); v[q][2 * jj + 1] = *(const f32x4*)(xL + o_ + 4); } }
; #pragma unroll
;         for (int q = 0; q < NR; ++q) { s[q] = 0.f;
; #pragma unroll
;             for (int j = 0; j < 4; ++j) s[q] += (v[q][j][0] + v[q][j][1]) + (v[q][j][2] + v[q][j][3]); }
; #pragma unroll
;         for (int o = 1; o < 64; o <<= 1) {
; #pragma unroll
;             for (int q = 0; q < NR; ++q) s[q] += __shfl_xor(s[q], o); }
; #pragma unroll
;         for (int q = 0; q < NR; ++q) { const float mean = s[q] * (1.0f / DM); s2[q] = 0.f;
; #pragma unroll
;             for (int j = 0; j < 4; ++j) { v[q][j] = v[q][j] - mean; s2[q] += (v[q][j][0] * v[q][j][0] + v[q][j][1] * v[q][j][1]) + (v[q][j][2] * v[q][j][2] + v[q][j][3] * v[q][j][3]); } }
; #pragma unroll
;         for (int o = 1; o < 64; o <<= 1) {
; #pragma unroll
;             for (int q = 0; q < NR; ++q) s2[q] += __shfl_xor(s2[q], o); }
; #pragma unroll
;         for (int jj = 0; jj < 2; ++jj) { const int col = 8 * lane + 512 * jj;
;             const f32x4 g0 = *(const f32x4*)(g + col), g1 = *(const f32x4*)(g + col + 4), b0 = *(const f32x4*)(b + col), b1 = *(const f32x4*)(b + col + 4);
; #pragma unroll
;             for (int q = 0; q < NR; ++q) { const int m = m0 + q * ngw; const float rstd = rsqrtf(s2[q] * (1.0f / DM) + EPSN);
;                 const f32x4 o0 = v[q][2 * jj] * rstd * g0 + b0, o1 = v[q][2 * jj + 1] * rstd * g1 + b1;
;                 if (xB) { v4u wx; wx.x = pk2(o0[0], o0[1]); wx.y = pk2(o0[2], o0[3]); wx.z = pk2(o1[0], o1[1]); wx.w = pk2(o1[2], o1[3]); *(v4u*)(xB + (size_t)m * DM + col) = wx; }
.LBB0_1228:
	s_or_b64 exec, exec, s[0:1]
	s_waitcnt lgkmcnt(0)
	v_mov_b32_e32 v2, v212
	s_barrier
	s_nop 0
	v_readfirstlane_b32 s0, v2
	s_ashr_i32 s16, s0, 6
	v_readlane_b32 s0, v255, 38
	v_readlane_b32 s1, v255, 39
	s_add_i32 s48, s16, s0
	v_readlane_b32 s0, v253, 41
	v_readlane_b32 s1, v253, 42
	s_lshl_b32 s84, s0, 10
	v_readlane_b32 s0, v253, 2
	s_lshl_b64 s[68:69], s[84:85], 2
	v_readlane_b32 s4, v253, 6
	v_readlane_b32 s5, v253, 7
	s_add_u32 s18, s4, s68
	v_readlane_b32 s6, v253, 8
	s_addc_u32 s19, s5, s69
	v_readlane_b32 s7, v253, 9
	s_add_u32 s20, s6, s68
	s_addc_u32 s21, s7, s69
	s_add_u32 s24, s63, 0x3000
	v_and_b32_e32 v160, 63, v2
	v_readlane_b32 s8, v253, 10
	v_readlane_b32 s9, v253, 11
	v_readlane_b32 s12, v253, 14
	s_addc_u32 s25, s62, 0
	s_add_i32 s0, s48, s54
	s_cmpk_gt_i32 s0, 0x7fff
	v_lshlrev_b32_e32 v34, 5, v160
	s_mov_b32 s22, s48
	v_readlane_b32 s12, v252, 47
	s_mov_b64 s[8:9], 0x1000
	v_readlane_b32 s1, v253, 3
	v_readlane_b32 s2, v253, 4
	v_readlane_b32 s3, v253, 5
	v_readlane_b32 s10, v253, 12
	v_readlane_b32 s11, v253, 13
	v_readlane_b32 s13, v253, 15
	v_readlane_b32 s14, v253, 16
	v_readlane_b32 s15, v253, 17
	s_mov_b64 s[2:3], s[18:19]
	s_mov_b64 s[26:27], s[20:21]
	s_mov_b64 s[28:29], s[24:25]
	s_mov_b32 s7, s48
	s_mov_b32 s23, 0
	s_mov_b32 s49, 0
.Llnx_entry:
	v_mbcnt_lo_u32_b32 v18, -1, 0
	v_mbcnt_hi_u32_b32 v18, -1, v18
	v_readlane_b32 s13, v253, 0
	v_lshlrev_b32_e32 v19, 4, v18
	v_lshlrev_b32_e32 v20, 5, v18
	s_nop 3
	s_lshl_b32 s13, s13, 3
	s_lshl_b32 s36, s13, 11
	s_lshl_b32 s37, s36, s23
	global_load_dwordx4 v[2:5], v20, s[2:3] offset:0
	global_load_dwordx4 v[6:9], v20, s[2:3] offset:16
	global_load_dwordx4 v[10:13], v20, s[2:3] offset:2048
	global_load_dwordx4 v[14:17], v20, s[2:3] offset:2064
	global_load_dwordx4 v[226:229], v20, s[26:27] offset:0
	global_load_dwordx4 v[230:233], v20, s[26:27] offset:16
	global_load_dwordx4 v[234:237], v20, s[26:27] offset:2048
	global_load_dwordx4 v[238:241], v20, s[26:27] offset:2064
	v_mov_b32_e32 v21, v19
	v_add_u32_e32 v22, s36, v21
	v_add_u32_e32 v23, s36, v22
	v_add_u32_e32 v24, s36, v23
	s_lshl_b32 s0, s36, 1
	v_mov_b32_e32 v102, v20
	v_add_u32_e32 v103, s0, v102
	v_add_u32_e32 v104, s0, v103
	v_add_u32_e32 v105, s0, v104
	s_lshl_b32 s0, s7, 11
	s_add_u32 s30, s64, s0
	s_addc_u32 s31, s65, 0
	s_lshl_b32 s0, s0, s23
	s_add_u32 s34, s92, s0
	s_addc_u32 s35, s93, 0
	s_cmp_eq_u32 s23, 0
	s_cbranch_scc0 .Llnx_nofill
	v_readfirstlane_b32 s0, v212
	s_nop 3
	s_lshr_b32 s0, s0, 6
	s_mul_i32 s1, s0, 0x6000
	s_add_u32 s28, s28, s1
	s_addc_u32 s29, s29, 0
	s_lshl_b32 s50, s0, 13
	s_mov_b32 m0, s50
	s_nop 0
	global_load_lds_dwordx4 v19, s[28:29] offset:0
	global_load_lds_dwordx4 v19, s[28:29] offset:1024
	global_load_lds_dwordx4 v19, s[28:29] offset:2048
	global_load_lds_dwordx4 v19, s[28:29] offset:3072
	s_add_u32 s28, s28, 0x1000
	s_addc_u32 s29, s29, 0
	s_add_i32 s50, s50, 0x1000
	s_mov_b32 m0, s50
	s_nop 0
	global_load_lds_dwordx4 v19, s[28:29] offset:0
	global_load_lds_dwordx4 v19, s[28:29] offset:1024
	global_load_lds_dwordx4 v19, s[28:29] offset:2048
	global_load_lds_dwordx4 v19, s[28:29] offset:3072
.Llnx_nofill:
	s_mul_i32 s0, s13, 3
	s_add_i32 s0, s0, s7
	s_cmp_lt_i32 s0, 0x8000
	s_cbranch_scc0 .Llnx_sync_done
	global_load_dwordx4 v[162:165], v21, s[30:31] offset:0
	global_load_dwordx4 v[166:169], v21, s[30:31] offset:1024
	global_load_dwordx4 v[170:173], v22, s[30:31] offset:0
	global_load_dwordx4 v[174:177], v22, s[30:31] offset:1024
	global_load_dwordx4 v[178:181], v23, s[30:31] offset:0
	global_load_dwordx4 v[182:185], v23, s[30:31] offset:1024
	global_load_dwordx4 v[186:189], v24, s[30:31] offset:0
	global_load_dwordx4 v[190:193], v24, s[30:31] offset:1024
	s_waitcnt vmcnt(0)
	s_barrier
	s_branch .Llnx_top
.Llnx_sync_done:
	s_waitcnt vmcnt(0)
	s_barrier
	s_branch .Llnx_done
.Llnx_top:
	v_lshlrev_b32_e32 v36, 16, v162
	v_and_b32_e32 v37, 0xffff0000, v162
	v_lshlrev_b32_e32 v38, 16, v163
	v_and_b32_e32 v39, 0xffff0000, v163
	v_lshlrev_b32_e32 v40, 16, v164
	v_and_b32_e32 v41, 0xffff0000, v164
	v_lshlrev_b32_e32 v42, 16, v165
	v_and_b32_e32 v43, 0xffff0000, v165
	v_lshlrev_b32_e32 v44, 16, v166
	v_and_b32_e32 v45, 0xffff0000, v166
	v_lshlrev_b32_e32 v46, 16, v167
	v_and_b32_e32 v47, 0xffff0000, v167
	v_lshlrev_b32_e32 v48, 16, v168
	v_and_b32_e32 v49, 0xffff0000, v168
	v_lshlrev_b32_e32 v50, 16, v169
	v_and_b32_e32 v51, 0xffff0000, v169
	v_lshlrev_b32_e32 v52, 16, v170
	v_and_b32_e32 v53, 0xffff0000, v170
	v_lshlrev_b32_e32 v54, 16, v171
	v_and_b32_e32 v55, 0xffff0000, v171
	v_lshlrev_b32_e32 v56, 16, v172
	v_and_b32_e32 v57, 0xffff0000, v172
	v_lshlrev_b32_e32 v58, 16, v173
	v_and_b32_e32 v59, 0xffff0000, v173
	v_lshlrev_b32_e32 v60, 16, v174
	v_and_b32_e32 v61, 0xffff0000, v174
	v_lshlrev_b32_e32 v62, 16, v175
	v_and_b32_e32 v63, 0xffff0000, v175
	v_lshlrev_b32_e32 v64, 16, v176
	v_and_b32_e32 v65, 0xffff0000, v176
	v_lshlrev_b32_e32 v66, 16, v177
	v_and_b32_e32 v67, 0xffff0000, v177
	v_lshlrev_b32_e32 v68, 16, v178
	v_and_b32_e32 v69, 0xffff0000, v178
	v_lshlrev_b32_e32 v70, 16, v179
	v_and_b32_e32 v71, 0xffff0000, v179
	v_lshlrev_b32_e32 v72, 16, v180
	v_and_b32_e32 v73, 0xffff0000, v180
	v_lshlrev_b32_e32 v74, 16, v181
	v_and_b32_e32 v75, 0xffff0000, v181
	v_lshlrev_b32_e32 v76, 16, v182
	v_and_b32_e32 v77, 0xffff0000, v182
	v_lshlrev_b32_e32 v78, 16, v183
	v_and_b32_e32 v79, 0xffff0000, v183
	v_lshlrev_b32_e32 v80, 16, v184
	v_and_b32_e32 v81, 0xffff0000, v184
	v_lshlrev_b32_e32 v82, 16, v185
	v_and_b32_e32 v83, 0xffff0000, v185
	v_lshlrev_b32_e32 v86, 16, v186
	v_and_b32_e32 v87, 0xffff0000, v186
	v_lshlrev_b32_e32 v88, 16, v187
	v_and_b32_e32 v89, 0xffff0000, v187
	v_lshlrev_b32_e32 v90, 16, v188
	v_and_b32_e32 v91, 0xffff0000, v188
	v_lshlrev_b32_e32 v92, 16, v189
	v_and_b32_e32 v93, 0xffff0000, v189
	v_lshlrev_b32_e32 v94, 16, v190
	v_and_b32_e32 v95, 0xffff0000, v190
	v_lshlrev_b32_e32 v96, 16, v191
	v_and_b32_e32 v97, 0xffff0000, v191
	v_lshlrev_b32_e32 v98, 16, v192
	v_and_b32_e32 v99, 0xffff0000, v192
	v_lshlrev_b32_e32 v100, 16, v193
	v_and_b32_e32 v101, 0xffff0000, v193
	s_mul_i32 s0, s13, 7
	s_add_i32 s0, s0, s7
	s_mov_b64 s[50:51], s[30:31]
	s_cmp_lt_i32 s0, 0x8000
	s_cbranch_scc0 .Llnx_nopf
	s_lshl_b32 s0, s36, 2
	s_add_u32 s30, s30, s0
	s_addc_u32 s31, s31, 0
	global_load_dwordx4 v[162:165], v21, s[30:31] offset:0
	global_load_dwordx4 v[166:169], v21, s[30:31] offset:1024
	global_load_dwordx4 v[170:173], v22, s[30:31] offset:0
	global_load_dwordx4 v[174:177], v22, s[30:31] offset:1024
	global_load_dwordx4 v[178:181], v23, s[30:31] offset:0
	global_load_dwordx4 v[182:185], v23, s[30:31] offset:1024
	global_load_dwordx4 v[186:189], v24, s[30:31] offset:0
	global_load_dwordx4 v[190:193], v24, s[30:31] offset:1024
; template <int NR> __device__ __forceinline__ void ln_lat_body(float* xL, const float* g, const float* b, const float* modp, bf16* U, int m0, int ngw, int lane, float* dummy, const bf16* vin, bf16* xB) {
;     ...
;         for (int q = 0; q < NR; ++q) { s[q] = 0.f;
; #pragma unroll
;             for (int j = 0; j < 4; ++j) s[q] += (v[q][j][0] + v[q][j][1]) + (v[q][j][2] + v[q][j][3]); }
; #pragma unroll
;         for (int o = 1; o < 64; o <<= 1) {
; #pragma unroll
;             for (int q = 0; q < NR; ++q) s[q] += __shfl_xor(s[q], o); }
; #pragma unroll
;         for (int q = 0; q < NR; ++q) { const float mean = s[q] * (1.0f / DM); s2[q] = 0.f;
; #pragma unroll
;             for (int j = 0; j < 4; ++j) { v[q][j] = v[q][j] - mean; s2[q] += (v[q][j][0] * v[q][j][0] + v[q][j][1] * v[q][j][1]) + (v[q][j][2] * v[q][j][2] + v[q][j][3] * v[q][j][3]); } }
.Llnx_nopf:
	v_add_f32_e32 v138, v36, v37
	v_add_f32_e32 v139, v38, v39
	v_add_f32_e32 v140, v40, v41
	v_add_f32_e32 v141, v42, v43
	v_add_f32_e32 v138, v138, v44
	v_add_f32_e32 v139, v139, v45
	v_add_f32_e32 v140, v140, v46
	v_add_f32_e32 v141, v141, v47
	v_add_f32_e32 v138, v138, v48
	v_add_f32_e32 v139, v139, v49
	v_add_f32_e32 v140, v140, v50
	v_add_f32_e32 v141, v141, v51
	v_add_f32_e32 v138, v138, v139
	v_add_f32_e32 v140, v140, v141
	v_add_f32_e32 v106, v138, v140
	v_add_f32_e32 v138, v52, v53
	v_add_f32_e32 v139, v54, v55
	v_add_f32_e32 v140, v56, v57
	v_add_f32_e32 v141, v58, v59
	v_add_f32_e32 v138, v138, v60
	v_add_f32_e32 v139, v139, v61
	v_add_f32_e32 v140, v140, v62
	v_add_f32_e32 v141, v141, v63
	v_add_f32_e32 v138, v138, v64
	v_add_f32_e32 v139, v139, v65
	v_add_f32_e32 v140, v140, v66
	v_add_f32_e32 v141, v141, v67
	v_add_f32_e32 v138, v138, v139
	v_add_f32_e32 v140, v140, v141
	v_add_f32_e32 v107, v138, v140
	v_add_f32_e32 v138, v68, v69
	v_add_f32_e32 v139, v70, v71
	v_add_f32_e32 v140, v72, v73
	v_add_f32_e32 v141, v74, v75
	v_add_f32_e32 v138, v138, v76
	v_add_f32_e32 v139, v139, v77
	v_add_f32_e32 v140, v140, v78
	v_add_f32_e32 v141, v141, v79
	v_add_f32_e32 v138, v138, v80
	v_add_f32_e32 v139, v139, v81
	v_add_f32_e32 v140, v140, v82
	v_add_f32_e32 v141, v141, v83
	v_add_f32_e32 v138, v138, v139
	v_add_f32_e32 v140, v140, v141
	v_add_f32_e32 v108, v138, v140
	v_add_f32_e32 v138, v86, v87
	v_add_f32_e32 v139, v88, v89
	v_add_f32_e32 v140, v90, v91
	v_add_f32_e32 v141, v92, v93
	v_add_f32_e32 v138, v138, v94
	v_add_f32_e32 v139, v139, v95
	v_add_f32_e32 v140, v140, v96
	v_add_f32_e32 v141, v141, v97
	v_add_f32_e32 v138, v138, v98
	v_add_f32_e32 v139, v139, v99
	v_add_f32_e32 v140, v140, v100
	v_add_f32_e32 v141, v141, v101
	v_add_f32_e32 v138, v138, v139
	v_add_f32_e32 v140, v140, v141
	v_add_f32_e32 v109, v138, v140
	ds_swizzle_b32 v138, v106 offset:0x041f
	ds_swizzle_b32 v139, v107 offset:0x041f
	ds_swizzle_b32 v140, v108 offset:0x041f
	ds_swizzle_b32 v141, v109 offset:0x041f
	s_waitcnt lgkmcnt(3)
	v_add_f32_e32 v106, v106, v138
	s_waitcnt lgkmcnt(2)
	v_add_f32_e32 v107, v107, v139
	s_waitcnt lgkmcnt(1)
	v_add_f32_e32 v108, v108, v140
	s_waitcnt lgkmcnt(0)
	v_add_f32_e32 v109, v109, v141
	ds_swizzle_b32 v138, v106 offset:0x081f
	ds_swizzle_b32 v139, v107 offset:0x081f
	ds_swizzle_b32 v140, v108 offset:0x081f
	ds_swizzle_b32 v141, v109 offset:0x081f
	s_waitcnt lgkmcnt(3)
	v_add_f32_e32 v106, v106, v138
	s_waitcnt lgkmcnt(2)
	v_add_f32_e32 v107, v107, v139
	s_waitcnt lgkmcnt(1)
	v_add_f32_e32 v108, v108, v140
	s_waitcnt lgkmcnt(0)
	v_add_f32_e32 v109, v109, v141
	ds_swizzle_b32 v138, v106 offset:0x101f
	ds_swizzle_b32 v139, v107 offset:0x101f
	ds_swizzle_b32 v140, v108 offset:0x101f
	ds_swizzle_b32 v141, v109 offset:0x101f
	s_waitcnt lgkmcnt(3)
	v_add_f32_e32 v106, v106, v138
	s_waitcnt lgkmcnt(2)
	v_add_f32_e32 v107, v107, v139
	s_waitcnt lgkmcnt(1)
	v_add_f32_e32 v108, v108, v140
	s_waitcnt lgkmcnt(0)
	v_add_f32_e32 v109, v109, v141
	ds_swizzle_b32 v138, v106 offset:0x201f
	ds_swizzle_b32 v139, v107 offset:0x201f
	ds_swizzle_b32 v140, v108 offset:0x201f
	ds_swizzle_b32 v141, v109 offset:0x201f
	s_waitcnt lgkmcnt(3)
	v_add_f32_e32 v106, v106, v138
	s_waitcnt lgkmcnt(2)
	v_add_f32_e32 v107, v107, v139
	s_waitcnt lgkmcnt(1)
	v_add_f32_e32 v108, v108, v140
	s_waitcnt lgkmcnt(0)
	v_add_f32_e32 v109, v109, v141
	ds_swizzle_b32 v138, v106 offset:0x401f
	ds_swizzle_b32 v139, v107 offset:0x401f
	ds_swizzle_b32 v140, v108 offset:0x401f
	ds_swizzle_b32 v141, v109 offset:0x401f
	s_waitcnt lgkmcnt(3)
	v_add_f32_e32 v106, v106, v138
	s_waitcnt lgkmcnt(2)
	v_add_f32_e32 v107, v107, v139
	s_waitcnt lgkmcnt(1)
	v_add_f32_e32 v108, v108, v140
	s_waitcnt lgkmcnt(0)
	v_add_f32_e32 v109, v109, v141
	v_mov_b32_e32 v138, v106
	v_mov_b32_e32 v139, v107
	v_mov_b32_e32 v140, v108
	v_mov_b32_e32 v141, v109
	s_nop 1
	v_permlane32_swap_b32_e32 v106, v138
	v_permlane32_swap_b32_e32 v107, v139
	v_permlane32_swap_b32_e32 v108, v140
	v_permlane32_swap_b32_e32 v109, v141
	v_add_f32_e32 v106, v106, v138
	v_add_f32_e32 v107, v107, v139
	v_add_f32_e32 v108, v108, v140
	v_add_f32_e32 v109, v109, v141
	v_mul_f32_e32 v106, 0x3a800000, v106
	v_mul_f32_e32 v107, 0x3a800000, v107
	v_mul_f32_e32 v108, 0x3a800000, v108
	v_mul_f32_e32 v109, 0x3a800000, v109
	v_sub_f32_e32 v36, v36, v106
	v_sub_f32_e32 v37, v37, v106
	v_sub_f32_e32 v38, v38, v106
	v_sub_f32_e32 v39, v39, v106
	v_sub_f32_e32 v40, v40, v106
	v_sub_f32_e32 v41, v41, v106
	v_sub_f32_e32 v42, v42, v106
	v_sub_f32_e32 v43, v43, v106
	v_sub_f32_e32 v44, v44, v106
	v_sub_f32_e32 v45, v45, v106
	v_sub_f32_e32 v46, v46, v106
	v_sub_f32_e32 v47, v47, v106
	v_sub_f32_e32 v48, v48, v106
	v_sub_f32_e32 v49, v49, v106
	v_sub_f32_e32 v50, v50, v106
	v_sub_f32_e32 v51, v51, v106
	v_sub_f32_e32 v52, v52, v107
	v_sub_f32_e32 v53, v53, v107
	v_sub_f32_e32 v54, v54, v107
	v_sub_f32_e32 v55, v55, v107
	v_sub_f32_e32 v56, v56, v107
	v_sub_f32_e32 v57, v57, v107
	v_sub_f32_e32 v58, v58, v107
	v_sub_f32_e32 v59, v59, v107
	v_sub_f32_e32 v60, v60, v107
	v_sub_f32_e32 v61, v61, v107
	v_sub_f32_e32 v62, v62, v107
	v_sub_f32_e32 v63, v63, v107
	v_sub_f32_e32 v64, v64, v107
	v_sub_f32_e32 v65, v65, v107
	v_sub_f32_e32 v66, v66, v107
	v_sub_f32_e32 v67, v67, v107
	v_sub_f32_e32 v68, v68, v108
	v_sub_f32_e32 v69, v69, v108
	v_sub_f32_e32 v70, v70, v108
	v_sub_f32_e32 v71, v71, v108
	v_sub_f32_e32 v72, v72, v108
	v_sub_f32_e32 v73, v73, v108
	v_sub_f32_e32 v74, v74, v108
	v_sub_f32_e32 v75, v75, v108
	v_sub_f32_e32 v76, v76, v108
	v_sub_f32_e32 v77, v77, v108
	v_sub_f32_e32 v78, v78, v108
	v_sub_f32_e32 v79, v79, v108
; template <int NR> __device__ __forceinline__ void ln_lat_body(float* xL, const float* g, const float* b, const float* modp, bf16* U, int m0, int ngw, int lane, float* dummy, const bf16* vin, bf16* xB) {
;     ...
;         for (int q = 0; q < NR; ++q) { const float mean = s[q] * (1.0f / DM); s2[q] = 0.f;
; #pragma unroll
;             for (int j = 0; j < 4; ++j) { v[q][j] = v[q][j] - mean; s2[q] += (v[q][j][0] * v[q][j][0] + v[q][j][1] * v[q][j][1]) + (v[q][j][2] * v[q][j][2] + v[q][j][3] * v[q][j][3]); } }
; #pragma unroll
;         for (int o = 1; o < 64; o <<= 1) {
; #pragma unroll
;             for (int q = 0; q < NR; ++q) s2[q] += __shfl_xor(s2[q], o); }
; #pragma unroll
;         for (int jj = 0; jj < 2; ++jj) { const int col = 8 * lane + 512 * jj;
;             const f32x4 g0 = *(const f32x4*)(g + col), g1 = *(const f32x4*)(g + col + 4), b0 = *(const f32x4*)(b + col), b1 = *(const f32x4*)(b + col + 4);
; #pragma unroll
;             for (int q = 0; q < NR; ++q) { const int m = m0 + q * ngw; const float rstd = rsqrtf(s2[q] * (1.0f / DM) + EPSN);
	v_sub_f32_e32 v80, v80, v108
	v_sub_f32_e32 v81, v81, v108
	v_sub_f32_e32 v82, v82, v108
	v_sub_f32_e32 v83, v83, v108
	v_sub_f32_e32 v86, v86, v109
	v_sub_f32_e32 v87, v87, v109
	v_sub_f32_e32 v88, v88, v109
	v_sub_f32_e32 v89, v89, v109
	v_sub_f32_e32 v90, v90, v109
	v_sub_f32_e32 v91, v91, v109
	v_sub_f32_e32 v92, v92, v109
	v_sub_f32_e32 v93, v93, v109
	v_sub_f32_e32 v94, v94, v109
	v_sub_f32_e32 v95, v95, v109
	v_sub_f32_e32 v96, v96, v109
	v_sub_f32_e32 v97, v97, v109
	v_sub_f32_e32 v98, v98, v109
	v_sub_f32_e32 v99, v99, v109
	v_sub_f32_e32 v100, v100, v109
	v_sub_f32_e32 v101, v101, v109
	v_mul_f32_e32 v138, v36, v36
	v_mul_f32_e32 v139, v37, v37
	v_mul_f32_e32 v140, v38, v38
	v_mul_f32_e32 v141, v39, v39
	v_fmac_f32_e32 v138, v40, v40
	v_fmac_f32_e32 v139, v41, v41
	v_fmac_f32_e32 v140, v42, v42
	v_fmac_f32_e32 v141, v43, v43
	v_fmac_f32_e32 v138, v44, v44
	v_fmac_f32_e32 v139, v45, v45
	v_fmac_f32_e32 v140, v46, v46
	v_fmac_f32_e32 v141, v47, v47
	v_fmac_f32_e32 v138, v48, v48
	v_fmac_f32_e32 v139, v49, v49
	v_fmac_f32_e32 v140, v50, v50
	v_fmac_f32_e32 v141, v51, v51
	v_add_f32_e32 v138, v138, v139
	v_add_f32_e32 v140, v140, v141
	v_add_f32_e32 v110, v138, v140
	v_mul_f32_e32 v138, v52, v52
	v_mul_f32_e32 v139, v53, v53
	v_mul_f32_e32 v140, v54, v54
	v_mul_f32_e32 v141, v55, v55
	v_fmac_f32_e32 v138, v56, v56
	v_fmac_f32_e32 v139, v57, v57
	v_fmac_f32_e32 v140, v58, v58
	v_fmac_f32_e32 v141, v59, v59
	v_fmac_f32_e32 v138, v60, v60
	v_fmac_f32_e32 v139, v61, v61
	v_fmac_f32_e32 v140, v62, v62
	v_fmac_f32_e32 v141, v63, v63
	v_fmac_f32_e32 v138, v64, v64
	v_fmac_f32_e32 v139, v65, v65
	v_fmac_f32_e32 v140, v66, v66
	v_fmac_f32_e32 v141, v67, v67
	v_add_f32_e32 v138, v138, v139
	v_add_f32_e32 v140, v140, v141
	v_add_f32_e32 v111, v138, v140
	v_mul_f32_e32 v138, v68, v68
	v_mul_f32_e32 v139, v69, v69
	v_mul_f32_e32 v140, v70, v70
	v_mul_f32_e32 v141, v71, v71
	v_fmac_f32_e32 v138, v72, v72
	v_fmac_f32_e32 v139, v73, v73
	v_fmac_f32_e32 v140, v74, v74
	v_fmac_f32_e32 v141, v75, v75
	v_fmac_f32_e32 v138, v76, v76
	v_fmac_f32_e32 v139, v77, v77
	v_fmac_f32_e32 v140, v78, v78
	v_fmac_f32_e32 v141, v79, v79
	v_fmac_f32_e32 v138, v80, v80
	v_fmac_f32_e32 v139, v81, v81
	v_fmac_f32_e32 v140, v82, v82
	v_fmac_f32_e32 v141, v83, v83
	v_add_f32_e32 v138, v138, v139
	v_add_f32_e32 v140, v140, v141
	v_add_f32_e32 v112, v138, v140
	v_mul_f32_e32 v138, v86, v86
	v_mul_f32_e32 v139, v87, v87
	v_mul_f32_e32 v140, v88, v88
	v_mul_f32_e32 v141, v89, v89
	v_fmac_f32_e32 v138, v90, v90
	v_fmac_f32_e32 v139, v91, v91
	v_fmac_f32_e32 v140, v92, v92
	v_fmac_f32_e32 v141, v93, v93
	v_fmac_f32_e32 v138, v94, v94
	v_fmac_f32_e32 v139, v95, v95
	v_fmac_f32_e32 v140, v96, v96
	v_fmac_f32_e32 v141, v97, v97
	v_fmac_f32_e32 v138, v98, v98
	v_fmac_f32_e32 v139, v99, v99
	v_fmac_f32_e32 v140, v100, v100
	v_fmac_f32_e32 v141, v101, v101
	v_add_f32_e32 v138, v138, v139
	v_add_f32_e32 v140, v140, v141
	v_add_f32_e32 v113, v138, v140
	ds_swizzle_b32 v138, v110 offset:0x041f
	ds_swizzle_b32 v139, v111 offset:0x041f
	ds_swizzle_b32 v140, v112 offset:0x041f
	ds_swizzle_b32 v141, v113 offset:0x041f
	s_waitcnt lgkmcnt(3)
	v_add_f32_e32 v110, v110, v138
	s_waitcnt lgkmcnt(2)
	v_add_f32_e32 v111, v111, v139
	s_waitcnt lgkmcnt(1)
	v_add_f32_e32 v112, v112, v140
	s_waitcnt lgkmcnt(0)
	v_add_f32_e32 v113, v113, v141
	ds_swizzle_b32 v138, v110 offset:0x081f
	ds_swizzle_b32 v139, v111 offset:0x081f
	ds_swizzle_b32 v140, v112 offset:0x081f
	ds_swizzle_b32 v141, v113 offset:0x081f
	s_waitcnt lgkmcnt(3)
	v_add_f32_e32 v110, v110, v138
	s_waitcnt lgkmcnt(2)
	v_add_f32_e32 v111, v111, v139
	s_waitcnt lgkmcnt(1)
	v_add_f32_e32 v112, v112, v140
	s_waitcnt lgkmcnt(0)
	v_add_f32_e32 v113, v113, v141
	ds_swizzle_b32 v138, v110 offset:0x101f
	ds_swizzle_b32 v139, v111 offset:0x101f
	ds_swizzle_b32 v140, v112 offset:0x101f
	ds_swizzle_b32 v141, v113 offset:0x101f
	s_waitcnt lgkmcnt(3)
	v_add_f32_e32 v110, v110, v138
	s_waitcnt lgkmcnt(2)
	v_add_f32_e32 v111, v111, v139
	s_waitcnt lgkmcnt(1)
	v_add_f32_e32 v112, v112, v140
	s_waitcnt lgkmcnt(0)
	v_add_f32_e32 v113, v113, v141
	ds_swizzle_b32 v138, v110 offset:0x201f
	ds_swizzle_b32 v139, v111 offset:0x201f
	ds_swizzle_b32 v140, v112 offset:0x201f
	ds_swizzle_b32 v141, v113 offset:0x201f
	s_waitcnt lgkmcnt(3)
	v_add_f32_e32 v110, v110, v138
	s_waitcnt lgkmcnt(2)
	v_add_f32_e32 v111, v111, v139
	s_waitcnt lgkmcnt(1)
	v_add_f32_e32 v112, v112, v140
	s_waitcnt lgkmcnt(0)
	v_add_f32_e32 v113, v113, v141
	ds_swizzle_b32 v138, v110 offset:0x401f
	ds_swizzle_b32 v139, v111 offset:0x401f
	ds_swizzle_b32 v140, v112 offset:0x401f
	ds_swizzle_b32 v141, v113 offset:0x401f
	s_waitcnt lgkmcnt(3)
	v_add_f32_e32 v110, v110, v138
	s_waitcnt lgkmcnt(2)
	v_add_f32_e32 v111, v111, v139
	s_waitcnt lgkmcnt(1)
	v_add_f32_e32 v112, v112, v140
	s_waitcnt lgkmcnt(0)
	v_add_f32_e32 v113, v113, v141
	v_mov_b32_e32 v138, v110
	v_mov_b32_e32 v139, v111
	v_mov_b32_e32 v140, v112
	v_mov_b32_e32 v141, v113
	s_nop 1
	v_permlane32_swap_b32_e32 v110, v138
	v_permlane32_swap_b32_e32 v111, v139
	v_permlane32_swap_b32_e32 v112, v140
	v_permlane32_swap_b32_e32 v113, v141
	v_add_f32_e32 v110, v110, v138
	v_add_f32_e32 v111, v111, v139
	v_add_f32_e32 v112, v112, v140
	v_add_f32_e32 v113, v113, v141
	v_mov_b32_e32 v142, 0x3a800000
	v_mov_b32_e32 v143, 0x358637bd
	v_fma_f32 v110, v110, v142, v143
	v_fma_f32 v111, v111, v142, v143
	v_fma_f32 v112, v112, v142, v143
	v_fma_f32 v113, v113, v142, v143
	v_rsq_f32_e32 v110, v110
	v_rsq_f32_e32 v111, v111
	v_rsq_f32_e32 v112, v112
	v_rsq_f32_e32 v113, v113
	s_nop 0
	s_cmp_eq_u32 s23, 0
	s_cbranch_scc0 .Llnx_epi_b
; __device__ __forceinline__ unsigned pk2(float lo, float hi) { return f2bf(lo) | (f2bf(hi) << 16); }
; template <int NR> __device__ __forceinline__ void ln_lat_body(float* xL, const float* g, const float* b, const float* modp, bf16* U, int m0, int ngw, int lane, float* dummy, const bf16* vin, bf16* xB) {
;     ...
;         for (int jj = 0; jj < 2; ++jj) { const int col = 8 * lane + 512 * jj;
;             const f32x4 g0 = *(const f32x4*)(g + col), g1 = *(const f32x4*)(g + col + 4), b0 = *(const f32x4*)(b + col), b1 = *(const f32x4*)(b + col + 4);
; #pragma unroll
;             for (int q = 0; q < NR; ++q) { const int m = m0 + q * ngw; const float rstd = rsqrtf(s2[q] * (1.0f / DM) + EPSN);
;                 const f32x4 o0 = v[q][2 * jj] * rstd * g0 + b0, o1 = v[q][2 * jj + 1] * rstd * g1 + b1;
;                 if (xB) { v4u wx; wx.x = pk2(o0[0], o0[1]); wx.y = pk2(o0[2], o0[3]); wx.z = pk2(o1[0], o1[1]); wx.w = pk2(o1[2], o1[3]); *(v4u*)(xB + (size_t)m * DM + col) = wx; }
;                 else { float* xo = (dummy ? dummy : xL) + (size_t)m * DM + col; *(f32x4*)xo = o0; *(f32x4*)(xo + 4) = o1; }
;                 if (modp) { const float* mp = modp + (size_t)(m >> 12) * 6144 + col; const f32x4 u0 = o0 * (*(const f32x4*)(mp + 1024) + 1.0f) + *(const f32x4*)mp, u1 = o1 * (*(const f32x4*)(mp + 1024 + 4) + 1.0f) + *(const f32x4*)(mp + 4);
;                     v4u w; w.x = pk2(u0[0], u0[1]); w.y = pk2(u0[2], u0[3]); w.z = pk2(u1[0], u1[1]); w.w = pk2(u1[2], u1[3]); *(v4u*)(U + (size_t)m * DM + col) = w; } } }
	s_mul_i32 s0, s13, 0
	s_add_i32 s0, s0, s7
	s_lshr_b32 s0, s0, 12
	s_lshl_b32 s0, s0, 13
	v_add_u32_e32 v158, s0, v20
	ds_read_b128 v[242:245], v158 offset:0
	ds_read_b128 v[246:249], v158 offset:16
	ds_read_b128 v[202:205], v158 offset:4096
	ds_read_b128 v[206:209], v158 offset:4112
	v_mul_f32_e32 v36, v36, v110
	v_mul_f32_e32 v37, v37, v110
	v_mul_f32_e32 v38, v38, v110
	v_mul_f32_e32 v39, v39, v110
	v_mul_f32_e32 v40, v40, v110
	v_mul_f32_e32 v41, v41, v110
	v_mul_f32_e32 v42, v42, v110
	v_mul_f32_e32 v43, v43, v110
	v_fma_f32 v36, v36, v2, v226
	v_fma_f32 v37, v37, v3, v227
	v_fma_f32 v38, v38, v4, v228
	v_fma_f32 v39, v39, v5, v229
	v_fma_f32 v40, v40, v6, v230
	v_fma_f32 v41, v41, v7, v231
	v_fma_f32 v42, v42, v8, v232
	v_fma_f32 v43, v43, v9, v233
	v_cvt_pk_bf16_f32 v146, v36, v37
	v_cvt_pk_bf16_f32 v147, v38, v39
	v_cvt_pk_bf16_f32 v148, v40, v41
	v_cvt_pk_bf16_f32 v149, v42, v43
	global_store_dwordx4 v21, v[146:149], s[34:35] offset:0
	s_waitcnt lgkmcnt(0)
	v_add_f32_e32 v202, 1.0, v202
	v_add_f32_e32 v203, 1.0, v203
	v_add_f32_e32 v204, 1.0, v204
	v_add_f32_e32 v205, 1.0, v205
	v_add_f32_e32 v206, 1.0, v206
	v_add_f32_e32 v207, 1.0, v207
	v_add_f32_e32 v208, 1.0, v208
	v_add_f32_e32 v209, 1.0, v209
	v_fma_f32 v130, v36, v202, v242
	v_fma_f32 v131, v37, v203, v243
	v_fma_f32 v132, v38, v204, v244
	v_fma_f32 v133, v39, v205, v245
	v_fma_f32 v134, v40, v206, v246
	v_fma_f32 v135, v41, v207, v247
	v_fma_f32 v136, v42, v208, v248
	v_fma_f32 v137, v43, v209, v249
	v_cvt_pk_bf16_f32 v150, v130, v131
	v_cvt_pk_bf16_f32 v151, v132, v133
	v_cvt_pk_bf16_f32 v152, v134, v135
	v_cvt_pk_bf16_f32 v153, v136, v137
	global_store_dwordx4 v21, v[150:153], s[50:51] offset:0
	ds_read_b128 v[242:245], v158 offset:2048
	ds_read_b128 v[246:249], v158 offset:2064
	ds_read_b128 v[202:205], v158 offset:6144
	ds_read_b128 v[206:209], v158 offset:6160
	v_mul_f32_e32 v44, v44, v110
	v_mul_f32_e32 v45, v45, v110
	v_mul_f32_e32 v46, v46, v110
	v_mul_f32_e32 v47, v47, v110
	v_mul_f32_e32 v48, v48, v110
	v_mul_f32_e32 v49, v49, v110
	v_mul_f32_e32 v50, v50, v110
	v_mul_f32_e32 v51, v51, v110
	v_fma_f32 v44, v44, v10, v234
	v_fma_f32 v45, v45, v11, v235
	v_fma_f32 v46, v46, v12, v236
	v_fma_f32 v47, v47, v13, v237
	v_fma_f32 v48, v48, v14, v238
	v_fma_f32 v49, v49, v15, v239
	v_fma_f32 v50, v50, v16, v240
	v_fma_f32 v51, v51, v17, v241
	v_cvt_pk_bf16_f32 v154, v44, v45
	v_cvt_pk_bf16_f32 v155, v46, v47
	v_cvt_pk_bf16_f32 v156, v48, v49
	v_cvt_pk_bf16_f32 v157, v50, v51
	global_store_dwordx4 v21, v[154:157], s[34:35] offset:1024
	s_waitcnt lgkmcnt(0)
	v_add_f32_e32 v202, 1.0, v202
	v_add_f32_e32 v203, 1.0, v203
	v_add_f32_e32 v204, 1.0, v204
	v_add_f32_e32 v205, 1.0, v205
	v_add_f32_e32 v206, 1.0, v206
	v_add_f32_e32 v207, 1.0, v207
	v_add_f32_e32 v208, 1.0, v208
	v_add_f32_e32 v209, 1.0, v209
	v_fma_f32 v130, v44, v202, v242
	v_fma_f32 v131, v45, v203, v243
	v_fma_f32 v132, v46, v204, v244
	v_fma_f32 v133, v47, v205, v245
	v_fma_f32 v134, v48, v206, v246
	v_fma_f32 v135, v49, v207, v247
	v_fma_f32 v136, v50, v208, v248
	v_fma_f32 v137, v51, v209, v249
	v_cvt_pk_bf16_f32 v194, v130, v131
	v_cvt_pk_bf16_f32 v195, v132, v133
	v_cvt_pk_bf16_f32 v196, v134, v135
	v_cvt_pk_bf16_f32 v197, v136, v137
	global_store_dwordx4 v21, v[194:197], s[50:51] offset:1024
	s_mul_i32 s0, s13, 1
	s_add_i32 s0, s0, s7
	s_lshr_b32 s0, s0, 12
	s_lshl_b32 s0, s0, 13
	v_add_u32_e32 v158, s0, v20
	ds_read_b128 v[242:245], v158 offset:0
	ds_read_b128 v[246:249], v158 offset:16
	ds_read_b128 v[202:205], v158 offset:4096
	ds_read_b128 v[206:209], v158 offset:4112
	v_mul_f32_e32 v52, v52, v111
	v_mul_f32_e32 v53, v53, v111
	v_mul_f32_e32 v54, v54, v111
	v_mul_f32_e32 v55, v55, v111
	v_mul_f32_e32 v56, v56, v111
	v_mul_f32_e32 v57, v57, v111
	v_mul_f32_e32 v58, v58, v111
	v_mul_f32_e32 v59, v59, v111
	v_fma_f32 v52, v52, v2, v226
	v_fma_f32 v53, v53, v3, v227
	v_fma_f32 v54, v54, v4, v228
	v_fma_f32 v55, v55, v5, v229
	v_fma_f32 v56, v56, v6, v230
	v_fma_f32 v57, v57, v7, v231
	v_fma_f32 v58, v58, v8, v232
	v_fma_f32 v59, v59, v9, v233
	v_cvt_pk_bf16_f32 v146, v52, v53
	v_cvt_pk_bf16_f32 v147, v54, v55
	v_cvt_pk_bf16_f32 v148, v56, v57
	v_cvt_pk_bf16_f32 v149, v58, v59
	global_store_dwordx4 v22, v[146:149], s[34:35] offset:0
	s_waitcnt lgkmcnt(0)
	v_add_f32_e32 v202, 1.0, v202
	v_add_f32_e32 v203, 1.0, v203
	v_add_f32_e32 v204, 1.0, v204
	v_add_f32_e32 v205, 1.0, v205
	v_add_f32_e32 v206, 1.0, v206
	v_add_f32_e32 v207, 1.0, v207
	v_add_f32_e32 v208, 1.0, v208
	v_add_f32_e32 v209, 1.0, v209
	v_fma_f32 v130, v52, v202, v242
	v_fma_f32 v131, v53, v203, v243
	v_fma_f32 v132, v54, v204, v244
	v_fma_f32 v133, v55, v205, v245
	v_fma_f32 v134, v56, v206, v246
	v_fma_f32 v135, v57, v207, v247
	v_fma_f32 v136, v58, v208, v248
	v_fma_f32 v137, v59, v209, v249
	v_cvt_pk_bf16_f32 v150, v130, v131
	v_cvt_pk_bf16_f32 v151, v132, v133
	v_cvt_pk_bf16_f32 v152, v134, v135
	v_cvt_pk_bf16_f32 v153, v136, v137
	global_store_dwordx4 v22, v[150:153], s[50:51] offset:0
	ds_read_b128 v[242:245], v158 offset:2048
	ds_read_b128 v[246:249], v158 offset:2064
	ds_read_b128 v[202:205], v158 offset:6144
	ds_read_b128 v[206:209], v158 offset:6160
	v_mul_f32_e32 v60, v60, v111
	v_mul_f32_e32 v61, v61, v111
	v_mul_f32_e32 v62, v62, v111
	v_mul_f32_e32 v63, v63, v111
	v_mul_f32_e32 v64, v64, v111
	v_mul_f32_e32 v65, v65, v111
	v_mul_f32_e32 v66, v66, v111
	v_mul_f32_e32 v67, v67, v111
	v_fma_f32 v60, v60, v10, v234
	v_fma_f32 v61, v61, v11, v235
	v_fma_f32 v62, v62, v12, v236
	v_fma_f32 v63, v63, v13, v237
	v_fma_f32 v64, v64, v14, v238
	v_fma_f32 v65, v65, v15, v239
	v_fma_f32 v66, v66, v16, v240
	v_fma_f32 v67, v67, v17, v241
	v_cvt_pk_bf16_f32 v154, v60, v61
	v_cvt_pk_bf16_f32 v155, v62, v63
	v_cvt_pk_bf16_f32 v156, v64, v65
	v_cvt_pk_bf16_f32 v157, v66, v67
	global_store_dwordx4 v22, v[154:157], s[34:35] offset:1024
	s_waitcnt lgkmcnt(0)
; __device__ __forceinline__ unsigned pk2(float lo, float hi) { return f2bf(lo) | (f2bf(hi) << 16); }
; template <int NR> __device__ __forceinline__ void ln_lat_body(float* xL, const float* g, const float* b, const float* modp, bf16* U, int m0, int ngw, int lane, float* dummy, const bf16* vin, bf16* xB) {
;     ...
;         for (int jj = 0; jj < 2; ++jj) { const int col = 8 * lane + 512 * jj;
;             const f32x4 g0 = *(const f32x4*)(g + col), g1 = *(const f32x4*)(g + col + 4), b0 = *(const f32x4*)(b + col), b1 = *(const f32x4*)(b + col + 4);
; #pragma unroll
;             for (int q = 0; q < NR; ++q) { const int m = m0 + q * ngw; const float rstd = rsqrtf(s2[q] * (1.0f / DM) + EPSN);
;                 const f32x4 o0 = v[q][2 * jj] * rstd * g0 + b0, o1 = v[q][2 * jj + 1] * rstd * g1 + b1;
;                 if (xB) { v4u wx; wx.x = pk2(o0[0], o0[1]); wx.y = pk2(o0[2], o0[3]); wx.z = pk2(o1[0], o1[1]); wx.w = pk2(o1[2], o1[3]); *(v4u*)(xB + (size_t)m * DM + col) = wx; }
;                 else { float* xo = (dummy ? dummy : xL) + (size_t)m * DM + col; *(f32x4*)xo = o0; *(f32x4*)(xo + 4) = o1; }
;                 if (modp) { const float* mp = modp + (size_t)(m >> 12) * 6144 + col; const f32x4 u0 = o0 * (*(const f32x4*)(mp + 1024) + 1.0f) + *(const f32x4*)mp, u1 = o1 * (*(const f32x4*)(mp + 1024 + 4) + 1.0f) + *(const f32x4*)(mp + 4);
;                     v4u w; w.x = pk2(u0[0], u0[1]); w.y = pk2(u0[2], u0[3]); w.z = pk2(u1[0], u1[1]); w.w = pk2(u1[2], u1[3]); *(v4u*)(U + (size_t)m * DM + col) = w; } } }
	v_add_f32_e32 v202, 1.0, v202
	v_add_f32_e32 v203, 1.0, v203
	v_add_f32_e32 v204, 1.0, v204
	v_add_f32_e32 v205, 1.0, v205
	v_add_f32_e32 v206, 1.0, v206
	v_add_f32_e32 v207, 1.0, v207
	v_add_f32_e32 v208, 1.0, v208
	v_add_f32_e32 v209, 1.0, v209
	v_fma_f32 v130, v60, v202, v242
	v_fma_f32 v131, v61, v203, v243
	v_fma_f32 v132, v62, v204, v244
	v_fma_f32 v133, v63, v205, v245
	v_fma_f32 v134, v64, v206, v246
	v_fma_f32 v135, v65, v207, v247
	v_fma_f32 v136, v66, v208, v248
	v_fma_f32 v137, v67, v209, v249
	v_cvt_pk_bf16_f32 v194, v130, v131
	v_cvt_pk_bf16_f32 v195, v132, v133
	v_cvt_pk_bf16_f32 v196, v134, v135
	v_cvt_pk_bf16_f32 v197, v136, v137
	global_store_dwordx4 v22, v[194:197], s[50:51] offset:1024
	s_mul_i32 s0, s13, 2
	s_add_i32 s0, s0, s7
	s_lshr_b32 s0, s0, 12
	s_lshl_b32 s0, s0, 13
	v_add_u32_e32 v158, s0, v20
	ds_read_b128 v[242:245], v158 offset:0
	ds_read_b128 v[246:249], v158 offset:16
	ds_read_b128 v[202:205], v158 offset:4096
	ds_read_b128 v[206:209], v158 offset:4112
	v_mul_f32_e32 v68, v68, v112
	v_mul_f32_e32 v69, v69, v112
	v_mul_f32_e32 v70, v70, v112
	v_mul_f32_e32 v71, v71, v112
	v_mul_f32_e32 v72, v72, v112
	v_mul_f32_e32 v73, v73, v112
	v_mul_f32_e32 v74, v74, v112
	v_mul_f32_e32 v75, v75, v112
	v_fma_f32 v68, v68, v2, v226
	v_fma_f32 v69, v69, v3, v227
	v_fma_f32 v70, v70, v4, v228
	v_fma_f32 v71, v71, v5, v229
	v_fma_f32 v72, v72, v6, v230
	v_fma_f32 v73, v73, v7, v231
	v_fma_f32 v74, v74, v8, v232
	v_fma_f32 v75, v75, v9, v233
	v_cvt_pk_bf16_f32 v146, v68, v69
	v_cvt_pk_bf16_f32 v147, v70, v71
	v_cvt_pk_bf16_f32 v148, v72, v73
	v_cvt_pk_bf16_f32 v149, v74, v75
	global_store_dwordx4 v23, v[146:149], s[34:35] offset:0
	s_waitcnt lgkmcnt(0)
	v_add_f32_e32 v202, 1.0, v202
	v_add_f32_e32 v203, 1.0, v203
	v_add_f32_e32 v204, 1.0, v204
	v_add_f32_e32 v205, 1.0, v205
	v_add_f32_e32 v206, 1.0, v206
	v_add_f32_e32 v207, 1.0, v207
	v_add_f32_e32 v208, 1.0, v208
	v_add_f32_e32 v209, 1.0, v209
	v_fma_f32 v130, v68, v202, v242
	v_fma_f32 v131, v69, v203, v243
	v_fma_f32 v132, v70, v204, v244
	v_fma_f32 v133, v71, v205, v245
	v_fma_f32 v134, v72, v206, v246
	v_fma_f32 v135, v73, v207, v247
	v_fma_f32 v136, v74, v208, v248
	v_fma_f32 v137, v75, v209, v249
	v_cvt_pk_bf16_f32 v150, v130, v131
	v_cvt_pk_bf16_f32 v151, v132, v133
	v_cvt_pk_bf16_f32 v152, v134, v135
	v_cvt_pk_bf16_f32 v153, v136, v137
	global_store_dwordx4 v23, v[150:153], s[50:51] offset:0
	ds_read_b128 v[242:245], v158 offset:2048
	ds_read_b128 v[246:249], v158 offset:2064
	ds_read_b128 v[202:205], v158 offset:6144
	ds_read_b128 v[206:209], v158 offset:6160
	v_mul_f32_e32 v76, v76, v112
	v_mul_f32_e32 v77, v77, v112
	v_mul_f32_e32 v78, v78, v112
	v_mul_f32_e32 v79, v79, v112
	v_mul_f32_e32 v80, v80, v112
	v_mul_f32_e32 v81, v81, v112
	v_mul_f32_e32 v82, v82, v112
	v_mul_f32_e32 v83, v83, v112
	v_fma_f32 v76, v76, v10, v234
	v_fma_f32 v77, v77, v11, v235
	v_fma_f32 v78, v78, v12, v236
	v_fma_f32 v79, v79, v13, v237
	v_fma_f32 v80, v80, v14, v238
	v_fma_f32 v81, v81, v15, v239
	v_fma_f32 v82, v82, v16, v240
	v_fma_f32 v83, v83, v17, v241
	v_cvt_pk_bf16_f32 v154, v76, v77
	v_cvt_pk_bf16_f32 v155, v78, v79
	v_cvt_pk_bf16_f32 v156, v80, v81
	v_cvt_pk_bf16_f32 v157, v82, v83
	global_store_dwordx4 v23, v[154:157], s[34:35] offset:1024
	s_waitcnt lgkmcnt(0)
	v_add_f32_e32 v202, 1.0, v202
	v_add_f32_e32 v203, 1.0, v203
	v_add_f32_e32 v204, 1.0, v204
	v_add_f32_e32 v205, 1.0, v205
	v_add_f32_e32 v206, 1.0, v206
	v_add_f32_e32 v207, 1.0, v207
	v_add_f32_e32 v208, 1.0, v208
	v_add_f32_e32 v209, 1.0, v209
	v_fma_f32 v130, v76, v202, v242
	v_fma_f32 v131, v77, v203, v243
	v_fma_f32 v132, v78, v204, v244
	v_fma_f32 v133, v79, v205, v245
	v_fma_f32 v134, v80, v206, v246
	v_fma_f32 v135, v81, v207, v247
	v_fma_f32 v136, v82, v208, v248
	v_fma_f32 v137, v83, v209, v249
	v_cvt_pk_bf16_f32 v194, v130, v131
	v_cvt_pk_bf16_f32 v195, v132, v133
	v_cvt_pk_bf16_f32 v196, v134, v135
	v_cvt_pk_bf16_f32 v197, v136, v137
	global_store_dwordx4 v23, v[194:197], s[50:51] offset:1024
	s_mul_i32 s0, s13, 3
	s_add_i32 s0, s0, s7
	s_lshr_b32 s0, s0, 12
	s_lshl_b32 s0, s0, 13
	v_add_u32_e32 v158, s0, v20
	ds_read_b128 v[242:245], v158 offset:0
	ds_read_b128 v[246:249], v158 offset:16
	ds_read_b128 v[202:205], v158 offset:4096
	ds_read_b128 v[206:209], v158 offset:4112
	v_mul_f32_e32 v86, v86, v113
	v_mul_f32_e32 v87, v87, v113
	v_mul_f32_e32 v88, v88, v113
	v_mul_f32_e32 v89, v89, v113
	v_mul_f32_e32 v90, v90, v113
	v_mul_f32_e32 v91, v91, v113
	v_mul_f32_e32 v92, v92, v113
	v_mul_f32_e32 v93, v93, v113
	v_fma_f32 v86, v86, v2, v226
	v_fma_f32 v87, v87, v3, v227
	v_fma_f32 v88, v88, v4, v228
	v_fma_f32 v89, v89, v5, v229
	v_fma_f32 v90, v90, v6, v230
	v_fma_f32 v91, v91, v7, v231
	v_fma_f32 v92, v92, v8, v232
	v_fma_f32 v93, v93, v9, v233
	v_cvt_pk_bf16_f32 v146, v86, v87
	v_cvt_pk_bf16_f32 v147, v88, v89
	v_cvt_pk_bf16_f32 v148, v90, v91
	v_cvt_pk_bf16_f32 v149, v92, v93
	global_store_dwordx4 v24, v[146:149], s[34:35] offset:0
	s_waitcnt lgkmcnt(0)
; __device__ __forceinline__ unsigned pk2(float lo, float hi) { return f2bf(lo) | (f2bf(hi) << 16); }
; template <int NR> __device__ __forceinline__ void ln_lat_body(float* xL, const float* g, const float* b, const float* modp, bf16* U, int m0, int ngw, int lane, float* dummy, const bf16* vin, bf16* xB) {
;     ...
;             for (int q = 0; q < NR; ++q) { const int m = m0 + q * ngw; const float rstd = rsqrtf(s2[q] * (1.0f / DM) + EPSN);
;                 const f32x4 o0 = v[q][2 * jj] * rstd * g0 + b0, o1 = v[q][2 * jj + 1] * rstd * g1 + b1;
;                 if (xB) { v4u wx; wx.x = pk2(o0[0], o0[1]); wx.y = pk2(o0[2], o0[3]); wx.z = pk2(o1[0], o1[1]); wx.w = pk2(o1[2], o1[3]); *(v4u*)(xB + (size_t)m * DM + col) = wx; }
;                 else { float* xo = (dummy ? dummy : xL) + (size_t)m * DM + col; *(f32x4*)xo = o0; *(f32x4*)(xo + 4) = o1; }
;                 if (modp) { const float* mp = modp + (size_t)(m >> 12) * 6144 + col; const f32x4 u0 = o0 * (*(const f32x4*)(mp + 1024) + 1.0f) + *(const f32x4*)mp, u1 = o1 * (*(const f32x4*)(mp + 1024 + 4) + 1.0f) + *(const f32x4*)(mp + 4);
;                     v4u w; w.x = pk2(u0[0], u0[1]); w.y = pk2(u0[2], u0[3]); w.z = pk2(u1[0], u1[1]); w.w = pk2(u1[2], u1[3]); *(v4u*)(U + (size_t)m * DM + col) = w; } } }
	v_add_f32_e32 v202, 1.0, v202
	v_add_f32_e32 v203, 1.0, v203
	v_add_f32_e32 v204, 1.0, v204
	v_add_f32_e32 v205, 1.0, v205
	v_add_f32_e32 v206, 1.0, v206
	v_add_f32_e32 v207, 1.0, v207
	v_add_f32_e32 v208, 1.0, v208
	v_add_f32_e32 v209, 1.0, v209
	v_fma_f32 v130, v86, v202, v242
	v_fma_f32 v131, v87, v203, v243
	v_fma_f32 v132, v88, v204, v244
	v_fma_f32 v133, v89, v205, v245
	v_fma_f32 v134, v90, v206, v246
	v_fma_f32 v135, v91, v207, v247
	v_fma_f32 v136, v92, v208, v248
	v_fma_f32 v137, v93, v209, v249
	v_cvt_pk_bf16_f32 v150, v130, v131
	v_cvt_pk_bf16_f32 v151, v132, v133
	v_cvt_pk_bf16_f32 v152, v134, v135
	v_cvt_pk_bf16_f32 v153, v136, v137
	global_store_dwordx4 v24, v[150:153], s[50:51] offset:0
	ds_read_b128 v[242:245], v158 offset:2048
	ds_read_b128 v[246:249], v158 offset:2064
	ds_read_b128 v[202:205], v158 offset:6144
	ds_read_b128 v[206:209], v158 offset:6160
	v_mul_f32_e32 v94, v94, v113
	v_mul_f32_e32 v95, v95, v113
	v_mul_f32_e32 v96, v96, v113
	v_mul_f32_e32 v97, v97, v113
	v_mul_f32_e32 v98, v98, v113
	v_mul_f32_e32 v99, v99, v113
	v_mul_f32_e32 v100, v100, v113
	v_mul_f32_e32 v101, v101, v113
	v_fma_f32 v94, v94, v10, v234
	v_fma_f32 v95, v95, v11, v235
	v_fma_f32 v96, v96, v12, v236
	v_fma_f32 v97, v97, v13, v237
	v_fma_f32 v98, v98, v14, v238
	v_fma_f32 v99, v99, v15, v239
	v_fma_f32 v100, v100, v16, v240
	v_fma_f32 v101, v101, v17, v241
	v_cvt_pk_bf16_f32 v154, v94, v95
	v_cvt_pk_bf16_f32 v155, v96, v97
	v_cvt_pk_bf16_f32 v156, v98, v99
	v_cvt_pk_bf16_f32 v157, v100, v101
	global_store_dwordx4 v24, v[154:157], s[34:35] offset:1024
	s_waitcnt lgkmcnt(0)
	v_add_f32_e32 v202, 1.0, v202
	v_add_f32_e32 v203, 1.0, v203
	v_add_f32_e32 v204, 1.0, v204
	v_add_f32_e32 v205, 1.0, v205
	v_add_f32_e32 v206, 1.0, v206
	v_add_f32_e32 v207, 1.0, v207
	v_add_f32_e32 v208, 1.0, v208
	v_add_f32_e32 v209, 1.0, v209
	v_fma_f32 v130, v94, v202, v242
	v_fma_f32 v131, v95, v203, v243
	v_fma_f32 v132, v96, v204, v244
	v_fma_f32 v133, v97, v205, v245
	v_fma_f32 v134, v98, v206, v246
	v_fma_f32 v135, v99, v207, v247
	v_fma_f32 v136, v100, v208, v248
	v_fma_f32 v137, v101, v209, v249
	v_cvt_pk_bf16_f32 v194, v130, v131
	v_cvt_pk_bf16_f32 v195, v132, v133
	v_cvt_pk_bf16_f32 v196, v134, v135
	v_cvt_pk_bf16_f32 v197, v136, v137
	global_store_dwordx4 v24, v[194:197], s[50:51] offset:1024
	s_branch .Llnx_next
; __device__ __forceinline__ unsigned pk2(float lo, float hi) { return f2bf(lo) | (f2bf(hi) << 16); }
; template <int NR> __device__ __forceinline__ void ln_lat_body(float* xL, const float* g, const float* b, const float* modp, bf16* U, int m0, int ngw, int lane, float* dummy, const bf16* vin, bf16* xB) {
;     ...
;             for (int q = 0; q < NR; ++q) { const int m = m0 + q * ngw; const float rstd = rsqrtf(s2[q] * (1.0f / DM) + EPSN);
;                 const f32x4 o0 = v[q][2 * jj] * rstd * g0 + b0, o1 = v[q][2 * jj + 1] * rstd * g1 + b1;
;                 if (xB) { v4u wx; wx.x = pk2(o0[0], o0[1]); wx.y = pk2(o0[2], o0[3]); wx.z = pk2(o1[0], o1[1]); wx.w = pk2(o1[2], o1[3]); *(v4u*)(xB + (size_t)m * DM + col) = wx; }
;                 else { float* xo = (dummy ? dummy : xL) + (size_t)m * DM + col; *(f32x4*)xo = o0; *(f32x4*)(xo + 4) = o1; }
;                 if (modp) { const float* mp = modp + (size_t)(m >> 12) * 6144 + col; const f32x4 u0 = o0 * (*(const f32x4*)(mp + 1024) + 1.0f) + *(const f32x4*)mp, u1 = o1 * (*(const f32x4*)(mp + 1024 + 4) + 1.0f) + *(const f32x4*)(mp + 4);
;                     v4u w; w.x = pk2(u0[0], u0[1]); w.y = pk2(u0[2], u0[3]); w.z = pk2(u1[0], u1[1]); w.w = pk2(u1[2], u1[3]); *(v4u*)(U + (size_t)m * DM + col) = w; } } }
;     }
; }
; __device__ __forceinline__ void ln_rows_lat(float* xL, const float* g, const float* b, const float* modp, bf16* U, int gw, int ngw, int lane, float* dummy, const bf16* vin, bf16* xB) {
;     int m0 = gw;
;     for (; m0 + 3 * ngw < ML; m0 += 4 * ngw) ln_lat_body<4>(xL, g, b, modp, U, m0, ngw, lane, dummy, vin, xB);
;     for (; m0 < ML; m0 += ngw) ln_lat_body<1>(xL, g, b, modp, U, m0, ngw, lane, dummy, vin, xB);
; }
.Llnx_epi_b:
	v_mul_f32_e32 v36, v36, v110
	v_mul_f32_e32 v37, v37, v110
	v_mul_f32_e32 v38, v38, v110
	v_mul_f32_e32 v39, v39, v110
	v_mul_f32_e32 v40, v40, v110
	v_mul_f32_e32 v41, v41, v110
	v_mul_f32_e32 v42, v42, v110
	v_mul_f32_e32 v43, v43, v110
	v_fma_f32 v36, v36, v2, v226
	v_fma_f32 v37, v37, v3, v227
	v_fma_f32 v38, v38, v4, v228
	v_fma_f32 v39, v39, v5, v229
	v_fma_f32 v40, v40, v6, v230
	v_fma_f32 v41, v41, v7, v231
	v_fma_f32 v42, v42, v8, v232
	v_fma_f32 v43, v43, v9, v233
	global_store_dwordx4 v102, v[36:39], s[34:35] offset:0
	global_store_dwordx4 v102, v[40:43], s[34:35] offset:16
	v_mul_f32_e32 v44, v44, v110
	v_mul_f32_e32 v45, v45, v110
	v_mul_f32_e32 v46, v46, v110
	v_mul_f32_e32 v47, v47, v110
	v_mul_f32_e32 v48, v48, v110
	v_mul_f32_e32 v49, v49, v110
	v_mul_f32_e32 v50, v50, v110
	v_mul_f32_e32 v51, v51, v110
	v_fma_f32 v44, v44, v10, v234
	v_fma_f32 v45, v45, v11, v235
	v_fma_f32 v46, v46, v12, v236
	v_fma_f32 v47, v47, v13, v237
	v_fma_f32 v48, v48, v14, v238
	v_fma_f32 v49, v49, v15, v239
	v_fma_f32 v50, v50, v16, v240
	v_fma_f32 v51, v51, v17, v241
	global_store_dwordx4 v102, v[44:47], s[34:35] offset:2048
	global_store_dwordx4 v102, v[48:51], s[34:35] offset:2064
	v_mul_f32_e32 v52, v52, v111
	v_mul_f32_e32 v53, v53, v111
	v_mul_f32_e32 v54, v54, v111
	v_mul_f32_e32 v55, v55, v111
	v_mul_f32_e32 v56, v56, v111
	v_mul_f32_e32 v57, v57, v111
	v_mul_f32_e32 v58, v58, v111
	v_mul_f32_e32 v59, v59, v111
	v_fma_f32 v52, v52, v2, v226
	v_fma_f32 v53, v53, v3, v227
	v_fma_f32 v54, v54, v4, v228
	v_fma_f32 v55, v55, v5, v229
	v_fma_f32 v56, v56, v6, v230
	v_fma_f32 v57, v57, v7, v231
	v_fma_f32 v58, v58, v8, v232
	v_fma_f32 v59, v59, v9, v233
	global_store_dwordx4 v103, v[52:55], s[34:35] offset:0
	global_store_dwordx4 v103, v[56:59], s[34:35] offset:16
	v_mul_f32_e32 v60, v60, v111
	v_mul_f32_e32 v61, v61, v111
	v_mul_f32_e32 v62, v62, v111
	v_mul_f32_e32 v63, v63, v111
	v_mul_f32_e32 v64, v64, v111
	v_mul_f32_e32 v65, v65, v111
	v_mul_f32_e32 v66, v66, v111
	v_mul_f32_e32 v67, v67, v111
	v_fma_f32 v60, v60, v10, v234
	v_fma_f32 v61, v61, v11, v235
	v_fma_f32 v62, v62, v12, v236
	v_fma_f32 v63, v63, v13, v237
	v_fma_f32 v64, v64, v14, v238
	v_fma_f32 v65, v65, v15, v239
	v_fma_f32 v66, v66, v16, v240
	v_fma_f32 v67, v67, v17, v241
	global_store_dwordx4 v103, v[60:63], s[34:35] offset:2048
	global_store_dwordx4 v103, v[64:67], s[34:35] offset:2064
	v_mul_f32_e32 v68, v68, v112
	v_mul_f32_e32 v69, v69, v112
	v_mul_f32_e32 v70, v70, v112
	v_mul_f32_e32 v71, v71, v112
	v_mul_f32_e32 v72, v72, v112
	v_mul_f32_e32 v73, v73, v112
	v_mul_f32_e32 v74, v74, v112
	v_mul_f32_e32 v75, v75, v112
	v_fma_f32 v68, v68, v2, v226
	v_fma_f32 v69, v69, v3, v227
	v_fma_f32 v70, v70, v4, v228
	v_fma_f32 v71, v71, v5, v229
	v_fma_f32 v72, v72, v6, v230
	v_fma_f32 v73, v73, v7, v231
	v_fma_f32 v74, v74, v8, v232
	v_fma_f32 v75, v75, v9, v233
	global_store_dwordx4 v104, v[68:71], s[34:35] offset:0
	global_store_dwordx4 v104, v[72:75], s[34:35] offset:16
	v_mul_f32_e32 v76, v76, v112
	v_mul_f32_e32 v77, v77, v112
	v_mul_f32_e32 v78, v78, v112
	v_mul_f32_e32 v79, v79, v112
	v_mul_f32_e32 v80, v80, v112
	v_mul_f32_e32 v81, v81, v112
	v_mul_f32_e32 v82, v82, v112
	v_mul_f32_e32 v83, v83, v112
	v_fma_f32 v76, v76, v10, v234
	v_fma_f32 v77, v77, v11, v235
	v_fma_f32 v78, v78, v12, v236
	v_fma_f32 v79, v79, v13, v237
	v_fma_f32 v80, v80, v14, v238
	v_fma_f32 v81, v81, v15, v239
	v_fma_f32 v82, v82, v16, v240
	v_fma_f32 v83, v83, v17, v241
	global_store_dwordx4 v104, v[76:79], s[34:35] offset:2048
	global_store_dwordx4 v104, v[80:83], s[34:35] offset:2064
	v_mul_f32_e32 v86, v86, v113
	v_mul_f32_e32 v87, v87, v113
	v_mul_f32_e32 v88, v88, v113
	v_mul_f32_e32 v89, v89, v113
	v_mul_f32_e32 v90, v90, v113
	v_mul_f32_e32 v91, v91, v113
	v_mul_f32_e32 v92, v92, v113
	v_mul_f32_e32 v93, v93, v113
	v_fma_f32 v86, v86, v2, v226
	v_fma_f32 v87, v87, v3, v227
	v_fma_f32 v88, v88, v4, v228
	v_fma_f32 v89, v89, v5, v229
	v_fma_f32 v90, v90, v6, v230
	v_fma_f32 v91, v91, v7, v231
	v_fma_f32 v92, v92, v8, v232
	v_fma_f32 v93, v93, v9, v233
	global_store_dwordx4 v105, v[86:89], s[34:35] offset:0
	global_store_dwordx4 v105, v[90:93], s[34:35] offset:16
	v_mul_f32_e32 v94, v94, v113
	v_mul_f32_e32 v95, v95, v113
	v_mul_f32_e32 v96, v96, v113
	v_mul_f32_e32 v97, v97, v113
	v_mul_f32_e32 v98, v98, v113
	v_mul_f32_e32 v99, v99, v113
	v_mul_f32_e32 v100, v100, v113
	v_mul_f32_e32 v101, v101, v113
	v_fma_f32 v94, v94, v10, v234
	v_fma_f32 v95, v95, v11, v235
	v_fma_f32 v96, v96, v12, v236
	v_fma_f32 v97, v97, v13, v237
	v_fma_f32 v98, v98, v14, v238
	v_fma_f32 v99, v99, v15, v239
	v_fma_f32 v100, v100, v16, v240
	v_fma_f32 v101, v101, v17, v241
	global_store_dwordx4 v105, v[94:97], s[34:35] offset:2048
	global_store_dwordx4 v105, v[98:101], s[34:35] offset:2064
.Llnx_next:
	s_lshl_b32 s0, s37, 2
	s_add_u32 s34, s34, s0
	s_addc_u32 s35, s35, 0
	s_lshl_b32 s0, s13, 2
	s_add_i32 s7, s7, s0
	s_mul_i32 s0, s13, 3
	s_add_i32 s0, s0, s7
	s_cmp_lt_i32 s0, 0x8000
	s_cbranch_scc0 .Llnx_done
	s_waitcnt vmcnt(16)
	s_branch .Llnx_top
.Llnx_done:
	s_cmp_eq_u32 s49, 0
	s_cbranch_scc1 .Llnx_ret0
	s_branch .Llnx_ret1
.Llnx_ret0:
	s_mov_b32 s22, s7

; #define IDS() int tid_ = threadIdx.x; asm volatile("" : "+v"(tid_)); const int lane_ = tid_ & 63, wave_ = __builtin_amdgcn_readfirstlane(tid_ >> 6); const int gw_ = vcu * NWAVES + wave_; (void)lane_; (void)gw_
; __device__ __forceinline__ void ln_rows_lat(float* xL, const float* g, const float* b, const float* modp, bf16* U, int gw, int ngw, int lane, float* dummy, const bf16* vin, bf16* xB) {
;     int m0 = gw;
;     for (; m0 + 3 * ngw < ML; m0 += 4 * ngw) ln_lat_body<4>(xL, g, b, modp, U, m0, ngw, lane, dummy, vin, xB);
;     for (; m0 < ML; m0 += ngw) ln_lat_body<1>(xL, g, b, modp, U, m0, ngw, lane, dummy, vin, xB);
; }
; __global__ void __launch_bounds__(NTHR, 2) trunk_fwd(Args a) {
;     ...
;         { IDS(); ln_rows(a.out, XC, mrows, a.ln2_g + l * DM, a.ln2_b + l * DM, need_ctx ? modl + 9 * 6144 : nullptr, U, gw_, ngw, lane_, nullptr, need_ctx ? RETC : nullptr, modl + 5 * 1024 + 8 * 6144, nullptr, U, need_ctx ? (bf16*)a.out : nullptr, 8); }
.LBB0_1770:
	s_or_b64 exec, exec, s[0:1]
	v_mov_b32_e32 v0, v212
	s_waitcnt lgkmcnt(0)
	s_barrier
	v_readlane_b32 s40, v255, 51
	v_readfirstlane_b32 s0, v0
	s_ashr_i32 s39, s0, 6
	v_readlane_b32 s0, v255, 38
	v_readlane_b32 s1, v255, 39
	s_add_i32 s38, s39, s0
	v_readlane_b32 s0, v253, 2
	v_readlane_b32 s8, v253, 10
	v_readlane_b32 s12, v253, 14
	v_readlane_b32 s9, v253, 11
	v_readlane_b32 s13, v253, 15
	s_add_u32 s8, s12, s68
	v_readlane_b32 s10, v253, 12
	v_readlane_b32 s14, v253, 16
	s_addc_u32 s9, s13, s69
	v_readlane_b32 s11, v253, 13
	v_readlane_b32 s15, v253, 17
	s_add_u32 s10, s14, s68
	v_readlane_b32 s1, v253, 3
	s_addc_u32 s11, s15, s69
	s_add_u32 s12, s84, 0x36000
	v_readlane_b32 s0, v253, 43
	s_addc_u32 s13, s70, 0
	v_readlane_b32 s1, v253, 44
	v_and_b32_e32 v144, 63, v0
	v_readlane_b32 s4, v253, 6
	v_readlane_b32 s5, v253, 7
	s_and_b64 s[0:1], s[0:1], exec
	v_readlane_b32 s6, v253, 8
	s_cselect_b32 s17, 0, s13
	s_cselect_b32 s16, 0, s12
	s_cselect_b32 s15, 0, s93
	s_cselect_b32 s14, 0, s92
	s_add_i32 s0, s38, s59
	v_lshlrev_b32_e32 v0, 4, v144
	v_readlane_b32 s42, v255, 56
	v_readlane_b32 s44, v255, 61
	v_readlane_b32 s4, v255, 42
	s_cmpk_gt_i32 s0, 0x7fff
	v_lshlrev_b32_e32 v28, 5, v144
	v_or_b32_e32 v26, 0x400, v0
	s_mov_b32 s12, s38
	v_readlane_b32 s41, v255, 52
	v_readlane_b32 s43, v255, 57
	v_readlane_b32 s45, v255, 62
	v_readlane_b32 s5, v255, 43
	s_mov_b32 s6, 0x6c00000
	s_mov_b64 s[68:69], 0x40000
	v_readlane_b32 s2, v253, 4
	v_readlane_b32 s3, v253, 5
	v_readlane_b32 s7, v253, 9
	s_mov_b64 s[2:3], s[8:9]
	s_mov_b64 s[26:27], s[10:11]
	s_mov_b64 s[28:29], s[16:17]
	s_mov_b32 s7, s38
	s_cmp_eq_u64 s[14:15], 0
	s_cselect_b32 s23, 1, 0
	s_mov_b32 s49, 1
	s_branch .Llnx_entry
.Llnx_ret1:
	s_mov_b32 s12, s7

; __global__ void __launch_bounds__(NTHR, 2) trunk_fwd(Args a) {
	.amdhsa_kernel _Z9trunk_fwd4Args
		.amdhsa_group_segment_fixed_size 0
		.amdhsa_private_segment_fixed_size 0
		.amdhsa_kernarg_size 464
		.amdhsa_user_sgpr_count 2
		.amdhsa_user_sgpr_dispatch_ptr 0
		.amdhsa_user_sgpr_queue_ptr 0
		.amdhsa_user_sgpr_kernarg_segment_ptr 1
		.amdhsa_user_sgpr_dispatch_id 0
		.amdhsa_user_sgpr_kernarg_preload_length 0
		.amdhsa_user_sgpr_kernarg_preload_offset 0
		.amdhsa_user_sgpr_private_segment_size 0
		.amdhsa_uses_dynamic_stack 0
		.amdhsa_enable_private_segment 0
		.amdhsa_system_sgpr_workgroup_id_x 1
		.amdhsa_system_sgpr_workgroup_id_y 0
		.amdhsa_system_sgpr_workgroup_id_z 0
		.amdhsa_system_sgpr_workgroup_info 0
		.amdhsa_system_vgpr_workitem_id 2
		.amdhsa_next_free_vgpr 256
		.amdhsa_next_free_sgpr 102
		.amdhsa_accum_offset 256
		.amdhsa_reserve_vcc 1
		.amdhsa_float_round_mode_32 0
		.amdhsa_float_round_mode_16_64 0
		.amdhsa_float_denorm_mode_32 3
		.amdhsa_float_denorm_mode_16_64 3
		.amdhsa_dx10_clamp 1
		.amdhsa_ieee_mode 1
		.amdhsa_fp16_overflow 0
		.amdhsa_tg_split 0
		.amdhsa_exception_fp_ieee_invalid_op 0
		.amdhsa_exception_fp_denorm_src 0
		.amdhsa_exception_fp_ieee_div_zero 0
		.amdhsa_exception_fp_ieee_overflow 0
		.amdhsa_exception_fp_ieee_underflow 0
		.amdhsa_exception_fp_ieee_inexact 0
		.amdhsa_exception_int_div_zero 0
	.end_amdhsa_kernel

; __global__ void __launch_bounds__(NTHR, 2) trunk_fwd(Args a) {
amdhsa.kernels:
  - .agpr_count:     0
    .args:
      - .offset:         0
        .size:           208
        .value_kind:     by_value
      - .offset:         208
        .size:           4
        .value_kind:     hidden_block_count_x
      - .offset:         212
        .size:           4
        .value_kind:     hidden_block_count_y
      - .offset:         216
        .size:           4
        .value_kind:     hidden_block_count_z
      - .offset:         220
        .size:           2
        .value_kind:     hidden_group_size_x
      - .offset:         222
        .size:           2
        .value_kind:     hidden_group_size_y
      - .offset:         224
        .size:           2
        .value_kind:     hidden_group_size_z
      - .offset:         226
        .size:           2
        .value_kind:     hidden_remainder_x
      - .offset:         228
        .size:           2
        .value_kind:     hidden_remainder_y
      - .offset:         230
        .size:           2
        .value_kind:     hidden_remainder_z
      - .offset:         248
        .size:           8
        .value_kind:     hidden_global_offset_x
      - .offset:         256
        .size:           8
        .value_kind:     hidden_global_offset_y
      - .offset:         264
        .size:           8
        .value_kind:     hidden_global_offset_z
      - .offset:         272
        .size:           2
        .value_kind:     hidden_grid_dims
      - .offset:         296
        .size:           8
        .value_kind:     hidden_multigrid_sync_arg
      - .offset:         328
        .size:           4
        .value_kind:     hidden_dynamic_lds_size
    .group_segment_fixed_size: 0
    .kernarg_segment_align: 8
    .kernarg_segment_size: 464
    .language:       OpenCL C
    .language_version:
      - 2
      - 0
    .max_flat_workgroup_size: 512
    .name:           _Z9trunk_fwd4Args
    .private_segment_fixed_size: 0
    .sgpr_count:     108
    .sgpr_spill_count: 255
    .symbol:         _Z9trunk_fwd4Args.kd
    .uniform_work_group_size: 1
    .uses_dynamic_stack: false
    .vgpr_count:     256
    .vgpr_spill_count: 0
    .wavefront_size: 64
